# window loop: lazy rescale (O/l rescaled only when a row max rises by more than 8), no per-tile packed multiplies
# baseline (speedup 1.0000x reference)
.LBB0_1362:
	v_max_f32_e32 v162, v162, v163
	v_sub_f32_e32 v164, v162, v0
	v_cmp_lt_f32_e32 vcc, 0x41000000, v164
	s_cbranch_vccnz .Lwin_rescale
	v_mov_b32_e32 v162, v0
	v_mov_b32_e32 v0, 1.0
.Lwin_cont:
	v_add3_u32 v163, s7, v200, v201
	v_add3_u32 v163, v163, v202, v203
	v_sub_f32_e32 v98, v98, v162
	v_sub_f32_e32 v99, v99, v162
	v_sub_f32_e32 v100, v100, v162
	v_sub_f32_e32 v101, v101, v162
	v_sub_f32_e32 v102, v102, v162
	v_sub_f32_e32 v103, v103, v162
	v_sub_f32_e32 v104, v104, v162
	v_sub_f32_e32 v105, v105, v162
	v_add_u32_e32 v178, v163, v204
	v_exp_f32_e32 v98, v98
	v_exp_f32_e32 v99, v99
	v_exp_f32_e32 v100, v100
	v_exp_f32_e32 v101, v101
	v_exp_f32_e32 v102, v102
	v_exp_f32_e32 v103, v103
	v_exp_f32_e32 v104, v104
	v_exp_f32_e32 v105, v105
	ds_read_b64_tr_b16 v[172:173], v178 offset:8192
	ds_read_b64_tr_b16 v[174:175], v178 offset:9216
	v_add_u32_e32 v163, v163, v205
	ds_read_b64_tr_b16 v[212:213], v163 offset:8192
	ds_read_b64_tr_b16 v[214:215], v163 offset:9216
	ds_read_b64_tr_b16 v[216:217], v178 offset:10240
	ds_read_b64_tr_b16 v[218:219], v178 offset:11264
	v_cvt_pk_bf16_f32 v164, v98, v99
	v_cvt_pk_bf16_f32 v165, v100, v101
	v_cvt_pk_bf16_f32 v166, v102, v103
	v_cvt_pk_bf16_f32 v167, v104, v105
	v_sub_f32_e32 v114, v114, v162
	v_sub_f32_e32 v115, v115, v162
	s_waitcnt lgkmcnt(4)
	v_mfma_f32_32x32x16_bf16 v[82:97], v[172:175], v[164:167], v[82:97]
	v_sub_f32_e32 v116, v116, v162
	v_sub_f32_e32 v117, v117, v162
	v_sub_f32_e32 v118, v118, v162
	v_sub_f32_e32 v119, v119, v162
	v_sub_f32_e32 v120, v120, v162
	v_sub_f32_e32 v121, v121, v162
	v_sub_f32_e32 v106, v106, v162
	s_waitcnt lgkmcnt(2)
	v_mfma_f32_32x32x16_bf16 v[66:81], v[212:215], v[164:167], v[66:81]
	v_sub_f32_e32 v122, v122, v162
	v_sub_f32_e32 v107, v107, v162
	v_sub_f32_e32 v123, v123, v162
	v_sub_f32_e32 v108, v108, v162
	v_sub_f32_e32 v124, v124, v162
	v_sub_f32_e32 v109, v109, v162
	v_sub_f32_e32 v125, v125, v162
	v_sub_f32_e32 v110, v110, v162
	v_sub_f32_e32 v126, v126, v162
	v_sub_f32_e32 v111, v111, v162
	v_sub_f32_e32 v127, v127, v162
	v_sub_f32_e32 v112, v112, v162
	v_sub_f32_e32 v128, v128, v162
	v_sub_f32_e32 v113, v113, v162
	v_sub_f32_e32 v129, v129, v162
	ds_read_b64_tr_b16 v[220:221], v163 offset:10240
	ds_read_b64_tr_b16 v[222:223], v163 offset:11264
	v_exp_f32_e32 v114, v114
	v_exp_f32_e32 v115, v115
	v_exp_f32_e32 v116, v116
	v_exp_f32_e32 v117, v117
	v_exp_f32_e32 v118, v118
	v_exp_f32_e32 v119, v119
	v_exp_f32_e32 v120, v120
	v_exp_f32_e32 v121, v121
	v_exp_f32_e32 v106, v106
	v_exp_f32_e32 v122, v122
	v_exp_f32_e32 v107, v107
	v_exp_f32_e32 v123, v123
	v_exp_f32_e32 v108, v108
	v_exp_f32_e32 v124, v124
	v_exp_f32_e32 v109, v109
	v_exp_f32_e32 v125, v125
	v_exp_f32_e32 v110, v110
	v_exp_f32_e32 v126, v126
	v_exp_f32_e32 v111, v111
	v_exp_f32_e32 v127, v127
	v_exp_f32_e32 v112, v112
	v_exp_f32_e32 v128, v128
	v_exp_f32_e32 v113, v113
	v_exp_f32_e32 v129, v129
	v_cvt_pk_bf16_f32 v168, v106, v107
	v_cvt_pk_bf16_f32 v169, v108, v109
	v_cvt_pk_bf16_f32 v170, v110, v111
	v_cvt_pk_bf16_f32 v171, v112, v113
	v_cvt_pk_bf16_f32 v208, v114, v115
	v_cvt_pk_bf16_f32 v209, v116, v117
	v_cvt_pk_bf16_f32 v210, v118, v119
	v_cvt_pk_bf16_f32 v211, v120, v121
	v_cvt_pk_bf16_f32 v172, v122, v123
	v_cvt_pk_bf16_f32 v173, v124, v125
	v_cvt_pk_bf16_f32 v174, v126, v127
	v_cvt_pk_bf16_f32 v175, v128, v129
	s_waitcnt lgkmcnt(2)
	v_mfma_f32_32x32x16_bf16 v[82:97], v[216:219], v[168:171], v[82:97]
	ds_read_b64_tr_b16 v[164:165], v178 offset:12288
	ds_read_b64_tr_b16 v[166:167], v178 offset:13312
	ds_read_b64_tr_b16 v[212:213], v163 offset:12288
	ds_read_b64_tr_b16 v[214:215], v163 offset:13312
	s_waitcnt lgkmcnt(4)
	v_mfma_f32_32x32x16_bf16 v[66:81], v[220:223], v[168:171], v[66:81]
	s_waitcnt lgkmcnt(2)
	v_mfma_f32_32x32x16_bf16 v[82:97], v[164:167], v[208:211], v[82:97]
	ds_read_b64_tr_b16 v[164:165], v178 offset:14336
	ds_read_b64_tr_b16 v[166:167], v178 offset:15360
	ds_read_b64_tr_b16 v[168:169], v163 offset:14336
	ds_read_b64_tr_b16 v[170:171], v163 offset:15360
	s_waitcnt lgkmcnt(4)
	v_mfma_f32_32x32x16_bf16 v[66:81], v[212:215], v[208:211], v[66:81]
	s_waitcnt lgkmcnt(2)
	v_mfma_f32_32x32x16_bf16 v[82:97], v[164:167], v[172:175], v[82:97]
	s_waitcnt lgkmcnt(0)
	v_mfma_f32_32x32x16_bf16 v[66:81], v[168:171], v[172:175], v[66:81]
	s_or_b32 s7, s73, s12
	s_cmp_lt_i32 s7, 0
	s_mov_b64 s[10:11], -1
	s_cbranch_scc0 .LBB0_1368
	s_and_b32 s7, s73, s12
	s_cmp_lt_i32 s7, 0
	s_cbranch_scc0 .LBB0_1365
	s_waitcnt vmcnt(0)
	s_mov_b64 s[10:11], 0

.Lwin_rescale:
	s_nop 1
	v_cndmask_b32_e32 v162, v0, v162, vcc
	v_sub_f32_e32 v164, v0, v162
	v_exp_f32_e32 v0, v164
	s_nop 0
	v_mul_f32_e32 v66, v66, v0
	v_mul_f32_e32 v67, v67, v0
	v_mul_f32_e32 v68, v68, v0
	v_mul_f32_e32 v69, v69, v0
	v_mul_f32_e32 v70, v70, v0
	v_mul_f32_e32 v71, v71, v0
	v_mul_f32_e32 v72, v72, v0
	v_mul_f32_e32 v73, v73, v0
	v_mul_f32_e32 v74, v74, v0
	v_mul_f32_e32 v75, v75, v0
	v_mul_f32_e32 v76, v76, v0
	v_mul_f32_e32 v77, v77, v0
	v_mul_f32_e32 v78, v78, v0
	v_mul_f32_e32 v79, v79, v0
	v_mul_f32_e32 v80, v80, v0
	v_mul_f32_e32 v81, v81, v0
	v_mul_f32_e32 v82, v82, v0
	v_mul_f32_e32 v83, v83, v0
	v_mul_f32_e32 v84, v84, v0
	v_mul_f32_e32 v85, v85, v0
	v_mul_f32_e32 v86, v86, v0
	v_mul_f32_e32 v87, v87, v0
	v_mul_f32_e32 v88, v88, v0
	v_mul_f32_e32 v89, v89, v0
	v_mul_f32_e32 v90, v90, v0
	v_mul_f32_e32 v91, v91, v0
	v_mul_f32_e32 v92, v92, v0
	v_mul_f32_e32 v93, v93, v0
	v_mul_f32_e32 v94, v94, v0
	v_mul_f32_e32 v95, v95, v0
	v_mul_f32_e32 v96, v96, v0
	v_mul_f32_e32 v97, v97, v0
	s_branch .Lwin_cont
